# pool phase: trailing-window ring init issues all halo-row loads together (were up to 15 serialized load round trips per thread)
# speedup vs baseline: 1.0171x; 1.0051x over previous
; __device__ __forceinline__ f32x2 ldx2(const bf16_t* p) { const unsigned w = *(const unsigned*)p; return (f32x2){__builtin_bit_cast(float, w << 16), __builtin_bit_cast(float, w & 0xffff0000u)}; }
; template <int W> __device__ __forceinline__ void pool_unit(const bf16_t* x, const LAS float* rs, f32x2 gn, bf16_t* Ag, size_t rb, int t0, int c, int g) {
;     f32x2 ring[16], hn_[16];
; #pragma unroll
;     for (int i = 0; i < 16; ++i) { const int t = t0 - 16 + i; ring[i] = (t >= 0) ? ldx2(x + (rb + t) * 1024 + c) * rs[i] * gn : (f32x2){0.f, 0.f}; }
;     f32x2 win = (f32x2){0.f, 0.f};
; #pragma unroll
;     for (int i = 16 - (W - 1); i < 16; ++i) win += ring[i];
; __device__ __forceinline__ void pool_phase(LAS unsigned char* lds, const bf16_t* x, const float* ssq, const float* gain, bf16_t* Ag, int G, int wg) {
;     ...
;         if (g == 0) pool_unit<2>(x, rs, gn, Ag, rb, t0, c, g); else if (g == 1) pool_unit<4>(x, rs, gn, Ag, rb, t0, c, g);
;         else if (g == 2) pool_unit<8>(x, rs, gn, Ag, rb, t0, c, g); else pool_unit<16>(x, rs, gn, Ag, rb, t0, c, g);
.LBB0_1177:
	s_or_b64 exec, exec, s[0:1]
	s_cmp_lg_u32 s16, 0
	s_cselect_b64 s[50:51], -1, 0
	s_waitcnt lgkmcnt(0)
	s_barrier
	s_and_saveexec_b64 s[0:1], s[42:43]
	s_xor_b64 s[52:53], exec, s[0:1]
	s_cbranch_execz .LBB0_1205
	v_cmp_lt_i32_e32 vcc, 1, v4
	s_mov_b64 s[54:55], 0
	s_mov_b64 s[56:57], 0
	s_and_saveexec_b64 s[0:1], vcc
	s_xor_b64 s[0:1], exec, s[0:1]
	s_cbranch_execz .LBB0_1194
	v_cmp_eq_u32_e32 vcc, 2, v4
	s_mov_b64 s[56:57], -1
	s_and_saveexec_b64 s[38:39], vcc
	s_cbranch_execz .LBB0_1210
	v_cndmask_b32_e64 v5, 0, 1, s[50:51]
	v_mov_b32_e32 v30, 0
	v_cmp_ne_u32_e64 s[44:45], 1, v5
	s_andn2_b64 vcc, exec, s[50:51]
	v_mov_b32_e32 v38, 0
	v_mov_b32_e32 v39, 0
	s_cbranch_vccnz .LBB0_1182
	s_add_i32 s56, s16, -5
	s_add_u32 s56, s48, s56
	s_addc_u32 s57, s49, 0
	s_lshl_b64 s[56:57], s[56:57], 11
	v_lshl_add_u64 v[158:159], v[6:7], 0, s[56:57]
	global_load_dword v129, v[158:159], off offset:-4096
	global_load_dword v131, v[158:159], off offset:-2048
	global_load_dword v133, v[158:159], off
	global_load_dword v135, v[158:159], off offset:2048
	s_add_i32 s56, s16, -2
	s_add_u32 s56, s48, s56
	s_addc_u32 s57, s49, 0
	s_lshl_b64 s[56:57], s[56:57], 11
	v_lshl_add_u64 v[160:161], v[6:7], 0, s[56:57]
	global_load_dword v137, v[160:161], off offset:-2048
	global_load_dword v139, v[160:161], off
	ds_read_b32 v128, v175 offset:36
	ds_read_b32 v130, v175 offset:40
	ds_read_b32 v132, v175 offset:44
	ds_read_b32 v134, v175 offset:48
	ds_read_b32 v136, v175 offset:52
	ds_read_b32 v138, v175 offset:56
	s_waitcnt vmcnt(0) lgkmcnt(0)
	v_lshlrev_b32_e32 v16, 16, v129
	v_and_b32_e32 v17, 0xffff0000, v129
	v_pk_mul_f32 v[14:15], v[128:129], v[16:17] op_sel_hi:[0,1]
	v_pk_mul_f32 v[38:39], v[2:3], v[14:15]
.LBB0_1182:
	s_and_b64 vcc, exec, s[44:45]
	v_mov_b32_e32 v31, 0
	s_cbranch_vccnz .LBB0_1184
	v_lshlrev_b32_e32 v16, 16, v131
	v_and_b32_e32 v17, 0xffff0000, v131
	v_pk_mul_f32 v[14:15], v[130:131], v[16:17] op_sel_hi:[0,1]
	v_pk_mul_f32 v[30:31], v[2:3], v[14:15]
.LBB0_1184:
	v_mov_b32_e32 v34, 0
	s_and_b64 vcc, exec, s[44:45]
	v_mov_b32_e32 v40, 0
	v_mov_b32_e32 v41, 0
	s_cbranch_vccnz .LBB0_1186
	v_lshlrev_b32_e32 v16, 16, v133
	v_and_b32_e32 v17, 0xffff0000, v133
	v_pk_mul_f32 v[14:15], v[132:133], v[16:17] op_sel_hi:[0,1]
	v_pk_mul_f32 v[40:41], v[2:3], v[14:15]
.LBB0_1186:
	s_and_b64 vcc, exec, s[44:45]
	v_mov_b32_e32 v35, 0
	s_cbranch_vccnz .LBB0_1188
	v_lshlrev_b32_e32 v16, 16, v135
	v_and_b32_e32 v17, 0xffff0000, v135
	v_pk_mul_f32 v[14:15], v[134:135], v[16:17] op_sel_hi:[0,1]
	v_pk_mul_f32 v[34:35], v[2:3], v[14:15]
.LBB0_1188:
	v_mov_b32_e32 v32, 0
	s_and_b64 vcc, exec, s[44:45]
	v_mov_b32_e32 v36, 0
	v_mov_b32_e32 v37, 0
	s_cbranch_vccnz .LBB0_1190
	v_lshlrev_b32_e32 v16, 16, v137
	v_and_b32_e32 v17, 0xffff0000, v137
	v_pk_mul_f32 v[14:15], v[136:137], v[16:17] op_sel_hi:[0,1]
	v_pk_mul_f32 v[36:37], v[2:3], v[14:15]
.LBB0_1190:
	s_and_b64 vcc, exec, s[44:45]
	v_mov_b32_e32 v33, 0
	s_cbranch_vccnz .LBB0_1192
	v_lshlrev_b32_e32 v16, 16, v139
	v_and_b32_e32 v17, 0xffff0000, v139
	v_pk_mul_f32 v[14:15], v[138:139], v[16:17] op_sel_hi:[0,1]
	v_pk_mul_f32 v[32:33], v[2:3], v[14:15]

; __device__ __forceinline__ f32x2 ldx2(const bf16_t* p) { const unsigned w = *(const unsigned*)p; return (f32x2){__builtin_bit_cast(float, w << 16), __builtin_bit_cast(float, w & 0xffff0000u)}; }
; template <int W> __device__ __forceinline__ void pool_unit(const bf16_t* x, const LAS float* rs, f32x2 gn, bf16_t* Ag, size_t rb, int t0, int c, int g) {
;     f32x2 ring[16], hn_[16];
; #pragma unroll
;     for (int i = 0; i < 16; ++i) { const int t = t0 - 16 + i; ring[i] = (t >= 0) ? ldx2(x + (rb + t) * 1024 + c) * rs[i] * gn : (f32x2){0.f, 0.f}; }
;     f32x2 win = (f32x2){0.f, 0.f};
; #pragma unroll
;     for (int i = 16 - (W - 1); i < 16; ++i) win += ring[i];
.LBB0_1197:
	v_cndmask_b32_e64 v5, 0, 1, s[50:51]
	v_mov_b32_e32 v22, 0
	v_cmp_ne_u32_e64 s[44:45], 1, v5
	s_andn2_b64 vcc, exec, s[50:51]
	v_mov_b32_e32 v26, 0
	v_mov_b32_e32 v27, 0
	s_cbranch_vccnz .LBB0_1199
	s_add_i32 s38, s16, -1
	s_add_u32 s38, s48, s38
	s_addc_u32 s39, s49, 0
	s_lshl_b64 s[38:39], s[38:39], 11
	v_lshl_add_u64 v[158:159], v[6:7], 0, s[38:39]
	global_load_dword v129, v[158:159], off offset:-4096
	global_load_dword v131, v[158:159], off offset:-2048
	global_load_dword v133, v[158:159], off
	ds_read_b32 v128, v175 offset:52
	ds_read_b32 v130, v175 offset:56
	ds_read_b32 v132, v175 offset:60
	s_waitcnt vmcnt(0) lgkmcnt(0)
	v_lshlrev_b32_e32 v16, 16, v129
	v_and_b32_e32 v17, 0xffff0000, v129
	v_pk_mul_f32 v[14:15], v[128:129], v[16:17] op_sel_hi:[0,1]
	v_pk_mul_f32 v[26:27], v[2:3], v[14:15]
.LBB0_1199:
	s_and_b64 vcc, exec, s[44:45]
	v_mov_b32_e32 v23, 0
	s_cbranch_vccnz .LBB0_1201
	v_lshlrev_b32_e32 v16, 16, v131
	v_and_b32_e32 v17, 0xffff0000, v131
	v_pk_mul_f32 v[14:15], v[130:131], v[16:17] op_sel_hi:[0,1]
	v_pk_mul_f32 v[22:23], v[2:3], v[14:15]
.LBB0_1201:
	s_and_b64 vcc, exec, s[44:45]
	s_cbranch_vccnz .LBB0_1203
	v_lshlrev_b32_e32 v16, 16, v133
	v_and_b32_e32 v17, 0xffff0000, v133
	v_pk_mul_f32 v[14:15], v[132:133], v[16:17] op_sel_hi:[0,1]
	v_pk_mul_f32 v[28:29], v[2:3], v[14:15]
	s_branch .LBB0_1204

; __device__ __forceinline__ f32x2 ldx2(const bf16_t* p) { const unsigned w = *(const unsigned*)p; return (f32x2){__builtin_bit_cast(float, w << 16), __builtin_bit_cast(float, w & 0xffff0000u)}; }
; template <int W> __device__ __forceinline__ void pool_unit(const bf16_t* x, const LAS float* rs, f32x2 gn, bf16_t* Ag, size_t rb, int t0, int c, int g) {
;     f32x2 ring[16], hn_[16];
; #pragma unroll
;     for (int i = 0; i < 16; ++i) { const int t = t0 - 16 + i; ring[i] = (t >= 0) ? ldx2(x + (rb + t) * 1024 + c) * rs[i] * gn : (f32x2){0.f, 0.f}; }
;     f32x2 win = (f32x2){0.f, 0.f};
; #pragma unroll
;     for (int i = 16 - (W - 1); i < 16; ++i) win += ring[i];
.LBB0_1212:
	v_cndmask_b32_e64 v5, 0, 1, s[50:51]
	v_mov_b32_e32 v38, 0
	v_cmp_ne_u32_e64 s[44:45], 1, v5
	s_andn2_b64 vcc, exec, s[50:51]
	v_mov_b32_e32 v68, 0
	v_mov_b32_e32 v69, 0
	s_cbranch_vccnz .LBB0_1214
	s_add_i32 s0, s16, -13
	s_add_u32 s0, s48, s0
	s_addc_u32 s1, s49, 0
	s_lshl_b64 s[0:1], s[0:1], 11
	v_lshl_add_u64 v[158:159], v[6:7], 0, s[0:1]
	global_load_dword v129, v[158:159], off offset:-4096
	global_load_dword v131, v[158:159], off offset:-2048
	global_load_dword v133, v[158:159], off
	global_load_dword v135, v[158:159], off offset:2048
	s_add_i32 s0, s16, -9
	s_add_u32 s0, s48, s0
	s_addc_u32 s1, s49, 0
	s_lshl_b64 s[0:1], s[0:1], 11
	v_lshl_add_u64 v[160:161], v[6:7], 0, s[0:1]
	global_load_dword v137, v[160:161], off offset:-4096
	global_load_dword v139, v[160:161], off offset:-2048
	global_load_dword v141, v[160:161], off
	global_load_dword v143, v[160:161], off offset:2048
	s_add_i32 s0, s16, -5
	s_add_u32 s0, s48, s0
	s_addc_u32 s1, s49, 0
	s_lshl_b64 s[0:1], s[0:1], 11
	v_lshl_add_u64 v[162:163], v[6:7], 0, s[0:1]
	global_load_dword v145, v[162:163], off offset:-4096
	global_load_dword v147, v[162:163], off offset:-2048
	global_load_dword v149, v[162:163], off
	global_load_dword v151, v[162:163], off offset:2048
	s_add_i32 s0, s16, -1
	s_add_u32 s0, s48, s0
	s_addc_u32 s1, s49, 0
	s_lshl_b64 s[0:1], s[0:1], 11
	v_lshl_add_u64 v[164:165], v[6:7], 0, s[0:1]
	global_load_dword v153, v[164:165], off offset:-4096
	global_load_dword v155, v[164:165], off offset:-2048
	global_load_dword v157, v[164:165], off
	ds_read_b32 v128, v175 offset:4
	ds_read_b32 v130, v175 offset:8
	ds_read_b32 v132, v175 offset:12
	ds_read_b32 v134, v175 offset:16
	ds_read_b32 v136, v175 offset:20
	ds_read_b32 v138, v175 offset:24
	ds_read_b32 v140, v175 offset:28
	ds_read_b32 v142, v175 offset:32
	ds_read_b32 v144, v175 offset:36
	ds_read_b32 v146, v175 offset:40
	ds_read_b32 v148, v175 offset:44
	ds_read_b32 v150, v175 offset:48
	ds_read_b32 v152, v175 offset:52
	ds_read_b32 v154, v175 offset:56
	ds_read_b32 v156, v175 offset:60
	s_waitcnt vmcnt(0) lgkmcnt(0)
	v_lshlrev_b32_e32 v16, 16, v129
	v_and_b32_e32 v17, 0xffff0000, v129
	v_pk_mul_f32 v[14:15], v[128:129], v[16:17] op_sel_hi:[0,1]
	v_pk_mul_f32 v[68:69], v[2:3], v[14:15]
.LBB0_1214:
	s_and_b64 vcc, exec, s[44:45]
	v_mov_b32_e32 v39, 0
	s_cbranch_vccnz .LBB0_1216
	v_lshlrev_b32_e32 v16, 16, v131
	v_and_b32_e32 v17, 0xffff0000, v131
	v_pk_mul_f32 v[14:15], v[130:131], v[16:17] op_sel_hi:[0,1]
	v_pk_mul_f32 v[38:39], v[2:3], v[14:15]
.LBB0_1216:
	v_mov_b32_e32 v46, 0
	s_and_b64 vcc, exec, s[44:45]
	v_mov_b32_e32 v70, 0
	v_mov_b32_e32 v71, 0
	s_cbranch_vccnz .LBB0_1218
	v_lshlrev_b32_e32 v16, 16, v133
	v_and_b32_e32 v17, 0xffff0000, v133
	v_pk_mul_f32 v[14:15], v[132:133], v[16:17] op_sel_hi:[0,1]
	v_pk_mul_f32 v[70:71], v[2:3], v[14:15]
.LBB0_1218:
	s_and_b64 vcc, exec, s[44:45]
	v_mov_b32_e32 v47, 0
	s_cbranch_vccnz .LBB0_1220
	v_lshlrev_b32_e32 v16, 16, v135
	v_and_b32_e32 v17, 0xffff0000, v135
	v_pk_mul_f32 v[14:15], v[134:135], v[16:17] op_sel_hi:[0,1]
	v_pk_mul_f32 v[46:47], v[2:3], v[14:15]
.LBB0_1220:
	v_mov_b32_e32 v42, 0
	s_and_b64 vcc, exec, s[44:45]
	v_mov_b32_e32 v66, 0
	v_mov_b32_e32 v67, 0
	s_cbranch_vccnz .LBB0_1222
	v_lshlrev_b32_e32 v16, 16, v137
	v_and_b32_e32 v17, 0xffff0000, v137
	v_pk_mul_f32 v[14:15], v[136:137], v[16:17] op_sel_hi:[0,1]
	v_pk_mul_f32 v[66:67], v[2:3], v[14:15]
.LBB0_1222:
	s_and_b64 vcc, exec, s[44:45]
	v_mov_b32_e32 v43, 0
	s_cbranch_vccnz .LBB0_1224
	v_lshlrev_b32_e32 v16, 16, v139
	v_and_b32_e32 v17, 0xffff0000, v139
	v_pk_mul_f32 v[14:15], v[138:139], v[16:17] op_sel_hi:[0,1]
	v_pk_mul_f32 v[42:43], v[2:3], v[14:15]
.LBB0_1224:
	v_mov_b32_e32 v40, 0
	s_and_b64 vcc, exec, s[44:45]
	v_mov_b32_e32 v64, 0
	v_mov_b32_e32 v65, 0
	s_cbranch_vccnz .LBB0_1226
	v_lshlrev_b32_e32 v16, 16, v141
	v_and_b32_e32 v17, 0xffff0000, v141
	v_pk_mul_f32 v[14:15], v[140:141], v[16:17] op_sel_hi:[0,1]
	v_pk_mul_f32 v[64:65], v[2:3], v[14:15]
.LBB0_1226:
	s_and_b64 vcc, exec, s[44:45]
	v_mov_b32_e32 v41, 0
	s_cbranch_vccnz .LBB0_1228
	v_lshlrev_b32_e32 v16, 16, v143
	v_and_b32_e32 v17, 0xffff0000, v143
	v_pk_mul_f32 v[14:15], v[142:143], v[16:17] op_sel_hi:[0,1]
	v_pk_mul_f32 v[40:41], v[2:3], v[14:15]
.LBB0_1228:
	v_mov_b32_e32 v36, 0
	s_and_b64 vcc, exec, s[44:45]
	v_mov_b32_e32 v62, 0
	v_mov_b32_e32 v63, 0
	s_cbranch_vccnz .LBB0_1230
	v_lshlrev_b32_e32 v16, 16, v145
	v_and_b32_e32 v17, 0xffff0000, v145
	v_pk_mul_f32 v[14:15], v[144:145], v[16:17] op_sel_hi:[0,1]
	v_pk_mul_f32 v[62:63], v[2:3], v[14:15]
.LBB0_1230:
	s_and_b64 vcc, exec, s[44:45]
	v_mov_b32_e32 v37, 0
	s_cbranch_vccnz .LBB0_1232
	v_lshlrev_b32_e32 v16, 16, v147
	v_and_b32_e32 v17, 0xffff0000, v147
	v_pk_mul_f32 v[14:15], v[146:147], v[16:17] op_sel_hi:[0,1]
	v_pk_mul_f32 v[36:37], v[2:3], v[14:15]
.LBB0_1232:
	v_mov_b32_e32 v34, 0
	s_and_b64 vcc, exec, s[44:45]
	v_mov_b32_e32 v60, 0
	v_mov_b32_e32 v61, 0
	s_cbranch_vccnz .LBB0_1234
	v_lshlrev_b32_e32 v16, 16, v149
	v_and_b32_e32 v17, 0xffff0000, v149
	v_pk_mul_f32 v[14:15], v[148:149], v[16:17] op_sel_hi:[0,1]
	v_pk_mul_f32 v[60:61], v[2:3], v[14:15]
.LBB0_1234:
	s_and_b64 vcc, exec, s[44:45]
	v_mov_b32_e32 v35, 0
	s_cbranch_vccnz .LBB0_1236
	v_lshlrev_b32_e32 v16, 16, v151
	v_and_b32_e32 v17, 0xffff0000, v151
	v_pk_mul_f32 v[14:15], v[150:151], v[16:17] op_sel_hi:[0,1]
	v_pk_mul_f32 v[34:35], v[2:3], v[14:15]
.LBB0_1236:
	v_mov_b32_e32 v32, 0
	s_and_b64 vcc, exec, s[44:45]
	v_mov_b32_e32 v58, 0
	v_mov_b32_e32 v59, 0
	s_cbranch_vccnz .LBB0_1238
	v_lshlrev_b32_e32 v16, 16, v153
	v_and_b32_e32 v17, 0xffff0000, v153
	v_pk_mul_f32 v[14:15], v[152:153], v[16:17] op_sel_hi:[0,1]
	v_pk_mul_f32 v[58:59], v[2:3], v[14:15]
.LBB0_1238:
	s_and_b64 vcc, exec, s[44:45]
	v_mov_b32_e32 v33, 0
	s_cbranch_vccnz .LBB0_1240
	v_lshlrev_b32_e32 v16, 16, v155
	v_and_b32_e32 v17, 0xffff0000, v155
	v_pk_mul_f32 v[14:15], v[154:155], v[16:17] op_sel_hi:[0,1]
	v_pk_mul_f32 v[32:33], v[2:3], v[14:15]
.LBB0_1240:
	s_and_b64 vcc, exec, s[44:45]
	s_cbranch_vccnz .LBB0_1242
	v_lshlrev_b32_e32 v16, 16, v157
	v_and_b32_e32 v17, 0xffff0000, v157
	v_pk_mul_f32 v[14:15], v[156:157], v[16:17] op_sel_hi:[0,1]
	v_pk_mul_f32 v[76:77], v[2:3], v[14:15]
	s_branch .LBB0_1243
